# attention phase: static s_setprio 1 for waves 4-7 (younger half, longest tile lists) for the duration of their attention items, reset after; on top of the attention trims
# speedup vs baseline: 1.0024x; 1.0024x over previous
; __global__ void __launch_bounds__(NTHR, 2) fwd_megakernel(Args args) {
;     ...
;         for (int pass = 0; pass < 2; ++pass) {
;         if ((pass ^ (wave & 1)) == 1) {
.LBB0_658:
	s_setprio 0
	v_readlane_b32 s30, v240, 38
	v_readlane_b32 s31, v240, 39

; #define LAS __attribute__((address_space(3)))
; __global__ void __launch_bounds__(NTHR, 2) fwd_megakernel(Args args) {
;     ...
;         } else {
;         constexpr int NQC = NB * NH * (SEQ / 64), NITEM = NQC + DECB * NH;
;         LAS unsigned char* ring = lds + 16384 + wave * 16384;
;         int rnd = 0;
;         for (int it = gw; it < NITEM; it += NGW, ++rnd) {
.LBB0_683:
	s_andn2_b64 vcc, exec, s[0:1]
	s_cbranch_vccnz .LBB0_659
	s_andn2_b64 vcc, exec, s[30:31]
	s_cbranch_vccnz .LBB0_659
	v_readlane_b32 s0, v240, 34
	s_mov_b32 s29, 0
	s_mov_b32 s30, s0
	s_bitcmp1_b32 s0, 2
	s_cbranch_scc0 .Lattn_noprio
	s_setprio 1
.Lattn_noprio:
	v_readlane_b32 s1, v240, 35
	s_branch .LBB0_687
